# GDN conv sweep: per-step full vmcnt drains in front of the RAW staging writes removed (raw rows are already drained at the step tail; one drain added before loop entry), redundant top-of-step barrier
# baseline (speedup 1.0000x reference)
; __device__ __forceinline__ void gdn_conv_sweep(Frame& F, int b, int hq) {
;     ...
;     { int tid = tid_; asm volatile("" : "+v"(tid)); GW_PREFETCH(0); }
; #pragma unroll 1
;     for (int st = 0; st < (TCX + TL) / 64; ++st) {
.LBB0_897:
	s_or_b64 exec, exec, s[12:13]
	s_lshl_b32 s41, s1, 11
	s_add_i32 s2, s41, 0x1000
	s_mov_b32 s1, s37
	s_mov_b32 s5, 0
	s_lshl_b32 s36, s4, 1
	s_waitcnt vmcnt(0)
	s_branch .LBB0_899

; #define LAS __attribute__((address_space(3)))
; #define LDS_BARRIER() do { asm volatile("s_waitcnt lgkmcnt(0)" ::: "memory"); __builtin_amdgcn_s_barrier(); asm volatile("" ::: "memory"); } while (0)
; __device__ __forceinline__ void gdn_conv_sweep(Frame& F, int b, int hq) {
;     ...
;     for (int st = 0; st < (TCX + TL) / 64; ++st) {
;         const int s0 = st * 64; const bool isctx = s0 < TCX; const int plo = isctx ? s0 : s0 - TCX, rowbase = isctx ? b * TCX : ROWS_C + b * TL;
;         int tid = tid_; asm volatile("" : "+v"(tid));
;         LDS_BARRIER();
; #pragma unroll
;         for (int n = 0; n < 9; ++n) { const int idx = tid + NTHREADS * n; if (idx < 68 * 64) *(LAS v4u*)(RAW + (idx >> 6) * 512 + (idx & 63) * 8) = rawp[n]; }
;         if (st + 1 < (TCX + TL) / 64) GW_PREFETCH(st + 1);
.LBB0_899:
	v_mov_b32_e32 v76, v112
	s_waitcnt lgkmcnt(0)
	s_nop 0
	v_lshlrev_b32_e32 v0, 4, v76
	v_and_b32_e32 v0, 0x3f0, v0
	s_movk_i32 s4, 0x1100
	v_lshlrev_b32_e32 v78, 3, v76
	v_add_u32_e32 v0, 0, v0
	v_cmp_gt_i32_e64 s[28:29], s4, v76
	s_and_saveexec_b64 s[12:13], s[28:29]
	s_cbranch_execz .LBB0_901
	v_and_b32_e32 v1, 0x7ffffe00, v78
	v_lshl_add_u32 v1, v1, 1, v0
	s_nop 0
	ds_write_b128 v1, v[4:7]
.LBB0_901:
	s_or_b64 exec, exec, s[12:13]
	s_movk_i32 s4, 0xf00
	v_add_u32_e32 v77, 0x200, v76
	v_cmp_gt_i32_e64 s[26:27], s4, v76
	s_and_saveexec_b64 s[12:13], s[26:27]
	s_cbranch_execz .LBB0_903
	v_lshlrev_b32_e32 v1, 4, v77
	v_and_b32_e32 v1, 0xfffffc00, v1
	v_add_u32_e32 v1, v0, v1
	s_nop 0
	ds_write_b128 v1, v[8:11]
.LBB0_903:
	s_or_b64 exec, exec, s[12:13]
	s_movk_i32 s4, 0xd00
	v_add_u32_e32 v75, 0x400, v76
	v_cmp_gt_i32_e64 s[24:25], s4, v76
	s_and_saveexec_b64 s[12:13], s[24:25]
	s_cbranch_execz .LBB0_905
	v_lshlrev_b32_e32 v1, 4, v75
	v_and_b32_e32 v1, 0xfffffc00, v1
	v_add_u32_e32 v1, v0, v1
	s_nop 0
	ds_write_b128 v1, v[12:15]
.LBB0_905:
	s_or_b64 exec, exec, s[12:13]
	s_movk_i32 s4, 0xb00
	v_add_u32_e32 v74, 0x600, v76
	v_cmp_gt_i32_e64 s[22:23], s4, v76
	s_and_saveexec_b64 s[12:13], s[22:23]
	s_cbranch_execz .LBB0_907
	v_lshlrev_b32_e32 v1, 4, v74
	v_and_b32_e32 v1, 0xfffffc00, v1
	v_add_u32_e32 v1, v0, v1
	s_nop 0
	ds_write_b128 v1, v[16:19]
.LBB0_907:
	s_or_b64 exec, exec, s[12:13]
	s_movk_i32 s4, 0x900
	v_add_u32_e32 v56, 0x800, v76
	v_cmp_gt_i32_e64 s[20:21], s4, v76
	s_and_saveexec_b64 s[12:13], s[20:21]
	s_cbranch_execz .LBB0_909
	v_lshlrev_b32_e32 v1, 4, v56
	v_and_b32_e32 v1, 0xfffffc00, v1
	v_add_u32_e32 v1, v0, v1
	s_nop 0
	ds_write_b128 v1, v[20:23]
.LBB0_909:
	s_or_b64 exec, exec, s[12:13]
	s_movk_i32 s4, 0x700
	v_add_u32_e32 v54, 0xa00, v76
	v_cmp_gt_i32_e64 s[18:19], s4, v76
	s_and_saveexec_b64 s[12:13], s[18:19]
	s_cbranch_execz .LBB0_911
	v_lshlrev_b32_e32 v1, 4, v54
	v_and_b32_e32 v1, 0xfffffc00, v1
	v_add_u32_e32 v1, v0, v1
	s_nop 0
	ds_write_b128 v1, v[24:27]
.LBB0_911:
	s_or_b64 exec, exec, s[12:13]
	s_movk_i32 s4, 0x500
	v_add_u32_e32 v52, 0xc00, v76
	v_cmp_gt_i32_e64 s[14:15], s4, v76
	s_and_saveexec_b64 s[12:13], s[14:15]
	s_cbranch_execz .LBB0_913
	v_lshlrev_b32_e32 v1, 4, v52
	v_and_b32_e32 v1, 0xfffffc00, v1
	v_add_u32_e32 v1, v0, v1
	s_nop 0
	ds_write_b128 v1, v[28:31]
.LBB0_913:
	s_or_b64 exec, exec, s[12:13]
	s_movk_i32 s4, 0x300
	v_add_u32_e32 v51, 0xe00, v76
	v_cmp_gt_i32_e64 s[12:13], s4, v76
	s_and_saveexec_b64 s[16:17], s[12:13]
	s_cbranch_execz .LBB0_915
	v_lshlrev_b32_e32 v1, 4, v51
	v_and_b32_e32 v1, 0xfffffc00, v1
	v_add_u32_e32 v1, v0, v1
	s_nop 0
	ds_write_b128 v1, v[32:35]
.LBB0_915:
	s_or_b64 exec, exec, s[16:17]
	v_add_u32_e32 v50, 0x1000, v76
	v_cmp_gt_i32_e32 vcc, s53, v76
	s_and_saveexec_b64 s[16:17], vcc
	s_cbranch_execz .LBB0_917
	v_lshlrev_b32_e32 v1, 4, v50
	v_and_b32_e32 v1, 0xfffffc00, v1
	v_add_u32_e32 v0, v0, v1
	s_nop 0
	ds_write_b128 v0, v[36:39]
.LBB0_917:
	s_or_b64 exec, exec, s[16:17]
	s_add_i32 s4, s5, 1
	s_cmp_eq_u32 s5, 35
	s_cbranch_scc1 .LBB0_937
	s_lshl_b32 s6, s4, 6
	s_add_i32 s16, s6, 0xffffff00
	s_cmp_lt_u32 s5, 3
	v_and_b32_e32 v1, 63, v76
	s_movk_i32 s7, 0x800
	s_cselect_b32 s50, s6, s16
	v_lshlrev_b32_e32 v0, 3, v1
	s_cselect_b32 s7, 0x100, s7
	s_cselect_b32 s6, s54, s2
	s_add_i32 s50, s50, -2
	v_add_u32_e32 v3, s3, v0
	s_nop 0
	v_add_u32_e32 v4, v0, v73
	v_add_u32_e32 v53, v0, v72
	v_ashrrev_i32_e32 v0, 6, v76
	v_add_u32_e32 v0, s50, v0
	v_cmp_lt_i32_e64 s[30:31], -1, v0
	s_and_b64 s[30:31], s[28:29], s[30:31]
	v_cmp_gt_i32_e64 s[28:29], s7, v0
	s_and_b64 s[30:31], s[30:31], s[28:29]
	v_mov_b32_e32 v8, v2
	v_mov_b32_e32 v9, v2
	v_cmp_gt_u32_e64 s[28:29], 32, v1
	v_mov_b32_e32 v10, v2
	v_mov_b32_e32 v11, v2
	v_cndmask_b32_e64 v55, v3, v4, s[28:29]
	v_mov_b64_e32 v[4:5], v[8:9]
	v_cmp_gt_u32_e64 s[16:17], 16, v1
	v_mov_b64_e32 v[6:7], v[10:11]
	s_and_saveexec_b64 s[28:29], s[30:31]
	s_cbranch_execz .LBB0_920
	v_add_u32_e32 v3, s6, v0
	v_mov_b64_e32 v[0:1], s[34:35]
	v_cndmask_b32_e64 v4, v55, v53, s[16:17]
	v_mad_i64_i32 v[0:1], s[30:31], v3, s90, v[0:1]
	v_mov_b32_e32 v5, v2
	v_lshl_add_u64 v[0:1], v[4:5], 1, v[0:1]
	global_load_dwordx4 v[4:7], v[0:1], off
